# S34 elementwise stage converted to packed-f32 VALU ops (same math, f32)
# speedup vs baseline: 1.0052x; 1.0052x over previous
.LBB0_179:
	s_or_b64 exec, exec, s[4:5]
	s_lshl_b32 s24, s45, 7
	s_add_i32 s14, s20, 0x1000
	s_add_i32 s15, s20, 0x2000
	s_add_i32 s4, s20, 0x7f80
	s_add_i32 s5, s20, 0x9a80
	s_add_i32 s17, s20, 0xc980
	s_add_i32 s23, s20, 0xd280
	s_add_i32 s24, s20, s24
	v_lshlrev_b32_e32 v5, 4, v81
	s_cmp_lg_u32 s45, 0
	v_add_u32_e32 v4, s24, v5
	s_cselect_b64 s[76:77], -1, 0
	s_bitcmp0_b32 s16, 6
	s_mov_b32 s24, 0x8880
	s_waitcnt vmcnt(42)
	v_cvt_pk_f16_f32 v36, v36, v37
	s_waitcnt vmcnt(41)
	v_cvt_pk_f16_f32 v37, v40, v41
	s_waitcnt vmcnt(36)
	v_cvt_pk_f16_f32 v41, v60, v61
	s_cselect_b32 s24, s24, 0x9180
	v_lshlrev_b32_e32 v61, 2, v77
	s_add_i32 s24, s20, s24
	v_cmp_lt_u32_e32 vcc, v61, v130
	v_cvt_pk_f16_f32 v44, v44, v45
	v_cvt_pk_f16_f32 v45, v48, v49
	v_cvt_pk_f16_f32 v48, v52, v53
	v_cvt_pk_f16_f32 v52, v68, v69
	v_cvt_pk_f16_f32 v68, v34, v35
	s_bitcmp0_b32 s16, 7
	v_cndmask_b32_e64 v34, 0, 1, vcc
	v_cmp_le_u32_e32 vcc, v61, v130
	v_cvt_pk_f16_f32 v42, v42, v43
	v_cvt_pk_f16_f32 v43, v46, v47
	v_cndmask_b32_e64 v35, 0, 1, vcc
	s_cselect_b64 vcc, -1, 0
	s_and_b64 s[26:27], vcc, exec
	s_cselect_b32 s25, s4, s5
	s_cmp_eq_u32 s45, 2
	s_mov_b32 s4, 0xcc80
	s_cselect_b32 s4, s4, 0xcf80
	s_add_i32 s16, s20, s4
	s_cmp_eq_u32 s45, 1
	v_cvt_pk_f16_f32 v46, v50, v51
	v_cvt_pk_f16_f32 v51, v70, v71
	v_cndmask_b32_e32 v70, v35, v34, vcc
	s_cselect_b64 s[4:5], -1, 0
	v_mul_u32_u24_e32 v34, 0x48, v130
	s_and_b64 s[26:27], s[4:5], exec
	v_lshlrev_b32_e32 v34, 1, v34
	v_lshlrev_b32_e32 v71, 4, v77
	s_cselect_b32 s14, s14, s15
	s_cselect_b32 s26, s17, s16
	s_cmp_eq_u32 s45, 0
	v_add_u32_e32 v35, s20, v34
	v_add3_u32 v162, s24, v34, v71
	v_add3_u32 v163, s25, v34, v71
	v_mul_u32_u24_e32 v34, 24, v130
	v_cvt_pk_f16_f32 v50, v66, v67
	v_cvt_pk_f16_f32 v66, v22, v23
	v_lshlrev_b32_e32 v155, 3, v77
	s_waitcnt vmcnt(29)
	v_cvt_pk_f16_f32 v22, v75, v86
	s_cselect_b32 s14, s20, s14
	s_cselect_b32 s23, s23, s26
	v_lshlrev_b32_e32 v75, 1, v34
	s_lshl_b64 s[24:25], s[46:47], 1
	v_mov_b32_e32 v60, s20
	v_add3_u32 v164, s23, v75, v155
	s_movk_i32 s23, 0xc0
	s_mul_hi_i32 s60, s18, 0x9000
	s_mul_i32 s61, s18, 0x9000
	s_add_u32 s18, s0, s24
	v_lshl_add_u32 v156, v82, 1, s20
	v_lshl_add_u32 v157, v82, 2, s14
	v_mad_u32_u24 v82, v77, s23, v60
	s_addc_u32 s23, s1, s25
	s_lshl_b32 s19, s19, 1
	v_and_b32_e32 v3, 63, v80
	v_mul_i32_i24_e32 v34, 0xffffffa0, v130
	s_add_u32 s18, s18, s19
	v_cvt_pk_f16_f32 v40, v56, v57
	v_lshrrev_b32_e32 v57, 3, v3
	v_add_u32_e32 v158, v35, v71
	v_add3_u32 v131, v35, v34, v155
	s_addc_u32 s19, s23, 0
	v_lshlrev_b32_e32 v34, 1, v130
	v_mov_b32_e32 v35, v2
	v_cmp_eq_u32_e64 s[14:15], 0, v81
	v_and_b32_e32 v160, 48, v80
	v_lshl_add_u64 v[80:81], s[18:19], 0, v[34:35]
	v_lshl_add_u32 v34, s45, 2, v57
	v_mad_u32_u24 v35, v34, s3, v60
	v_mul_u32_u24_e32 v60, 0x90, v34
	v_mov_b32_e32 v34, -1
	v_add_u32_sdwa v167, v76, v34 dst_sel:DWORD dst_unused:UNUSED_PAD src0_sel:BYTE_0 src1_sel:DWORD
	v_lshlrev_b32_e32 v34, 1, v3
	v_cvt_pk_f16_f32 v47, v62, v63
	v_cvt_f16_f32_e32 v62, v27
	v_cvt_f16_f32_e32 v56, v17
	s_waitcnt vmcnt(16)
	v_cvt_pk_f16_f32 v17, v100, v104
	s_waitcnt vmcnt(8)
	v_cvt_pk_f16_f32 v27, v105, v107
	s_movk_i32 s18, 0xff48
	s_lshl_b32 s46, s22, 11
	v_add_u32_e32 v168, s20, v34
	v_sub_u32_e32 v171, 0, v34
	v_cvt_f32_f16_e32 v104, v36
	v_cvt_f32_f16_sdwa v105, v36 dst_sel:DWORD dst_unused:UNUSED_PAD src0_sel:WORD_1
	v_lshl_or_b32 v34, v77, 10, v74
	v_or_b32_e32 v36, 1, v61
	v_cvt_pk_f16_f32 v38, v38, v39
	v_cvt_pk_f16_f32 v39, v54, v55
	v_mad_i32_i24 v166, v77, s18, v82
	s_add_i32 s46, s46, s21
	v_mad_u32_u24 v169, v3, 48, s20
	s_movk_i32 s18, 0xffd4
	v_cvt_f32_f16_e32 v124, v37
	v_cvt_f32_f16_sdwa v125, v37 dst_sel:DWORD dst_unused:UNUSED_PAD src0_sel:WORD_1
	v_add_u32_e32 v184, s20, v34
	v_lshl_or_b32 v34, v36, 8, v74
	v_or_b32_e32 v37, 2, v61
	v_mad_i32_i24 v170, v3, s18, v169
	v_cvt_f32_f16_e32 v120, v39
	v_cvt_f32_f16_sdwa v121, v39 dst_sel:DWORD dst_unused:UNUSED_PAD src0_sel:WORD_1
	v_add_u32_e32 v186, s20, v34
	v_lshl_or_b32 v34, v37, 8, v74
	v_or_b32_e32 v39, 3, v61
	s_and_b64 s[18:19], s[12:13], exec
	v_cvt_pk_f16_f32 v53, v72, v73
	v_lshlrev_b32_e32 v72, 2, v3
	v_add_u32_e32 v187, s20, v34
	v_lshl_or_b32 v34, v39, 8, v74
	s_cselect_b32 s63, 0, 0xf00
	s_movk_i32 s18, 0xe00
	v_add_u32_e32 v188, s20, v34
	s_cselect_b32 s66, 0x100, s18
	s_movk_i32 s18, 0xd00
	v_or_b32_e32 v34, s63, v72
	s_cselect_b32 s67, 0x200, s18
	s_movk_i32 s18, 0xc00
	v_add_u32_e32 v189, s20, v34
	v_or_b32_e32 v34, s66, v72
	s_cselect_b32 s72, 0x300, s18
	s_movk_i32 s18, 0xb00
	v_add_u32_e32 v190, s20, v34
	v_or_b32_e32 v34, s67, v72
	s_cselect_b32 s73, 0x400, s18
	s_movk_i32 s18, 0x500
	v_add_u32_e32 v191, s20, v34
	v_or_b32_e32 v34, s72, v72
	s_cselect_b32 s74, s18, 0xa00
	s_movk_i32 s18, 0x900
	v_add_u32_e32 v192, s20, v34
	v_or_b32_e32 v34, s73, v72
	s_cselect_b32 s75, 0x600, s18
	s_movk_i32 s18, 0x700
	v_add_u32_e32 v193, s20, v34
	v_or_b32_e32 v34, s74, v72
	s_cselect_b32 s78, s18, 0x800
	v_add_u32_e32 v194, s20, v34
	v_or_b32_e32 v34, s75, v72
	s_movk_i32 s18, 0x1c0
	v_add_u32_e32 v195, s20, v34
	v_or_b32_e32 v34, s78, v72
	s_cselect_b32 s18, 0x200, s18
	v_add_u32_e32 v199, s20, v34
	v_or_b32_e32 v34, s18, v3
	s_movk_i32 s18, 0x240
	s_cselect_b32 s18, s18, 0x180
	v_lshl_add_u32 v200, v34, 2, s20
	v_or_b32_e32 v34, s18, v3
	s_movk_i32 s18, 0x140
	s_cselect_b32 s18, 0x280, s18
	v_lshl_add_u32 v201, v34, 2, s20
	v_or_b32_e32 v34, s18, v3
	s_movk_i32 s18, 0x2c0
	s_cselect_b32 s18, s18, 0x100
	v_lshl_add_u32 v202, v34, 2, s20
	v_or_b32_e32 v34, s18, v3
	s_movk_i32 s18, 0x300
	s_cselect_b32 s18, s18, 0xc0
	v_lshl_add_u32 v203, v34, 2, s20
	v_or_b32_e32 v34, s18, v3
	s_movk_i32 s18, 0x340
	s_cselect_b32 s18, s18, 0x80
	v_lshl_add_u32 v204, v34, 2, s20
	v_or_b32_e32 v34, s18, v3
	s_cselect_b32 s18, 0x380, 64
	v_lshl_add_u32 v205, v34, 2, s20
	v_or_b32_e32 v34, s18, v3
	s_cselect_b32 s18, 0x3c0, 0
	v_lshl_add_u32 v206, v34, 2, s20
	v_or_b32_e32 v34, s18, v3
	v_lshl_add_u32 v207, v34, 2, s20
	s_lshl_b32 s18, s18, 2
	v_and_b32_e32 v34, 1, v70
	v_add_u32_e32 v159, s20, v72
	v_add_u32_e32 v161, s20, v160
	v_mad_u32_u24 v132, v83, 48, s20
	v_add_u32_e32 v172, s20, v75
	v_lshl_add_u32 v182, v57, 2, s20
	v_add_u32_e32 v185, s20, v71
	s_add_i32 s20, s20, s18
	v_cmp_eq_u32_e64 s[18:19], 1, v34
	v_cndmask_b32_e32 v34, v61, v36, vcc
	v_cmp_lt_u32_e64 s[22:23], v37, v130
	v_add_u32_e32 v208, s20, v72
	v_cmp_gt_u32_e64 s[20:21], v130, v34
	v_cndmask_b32_e64 v34, 0, 1, s[22:23]
	v_cmp_le_u32_e64 s[22:23], v37, v130
	v_cvt_f32_f16_e32 v118, v38
	v_cvt_f32_f16_sdwa v119, v38 dst_sel:DWORD dst_unused:UNUSED_PAD src0_sel:WORD_1
	v_cndmask_b32_e64 v38, 0, 1, s[22:23]
	v_cndmask_b32_e32 v34, v38, v34, vcc
	v_and_b32_e32 v34, 1, v34
	v_cmp_lt_u32_e64 s[24:25], v39, v130
	v_cmp_eq_u32_e64 s[22:23], 1, v34
	v_cmp_gt_u32_e64 s[16:17], 32, v3
	v_cndmask_b32_e64 v34, 0, 1, s[24:25]
	v_cmp_le_u32_e64 s[24:25], v39, v130
	v_mul_i32_i24_e32 v76, 0xffffffd2, v3
	v_cmp_gt_u32_e64 s[26:27], 16, v3
	v_cndmask_b32_e64 v38, 0, 1, s[24:25]
	v_cndmask_b32_e32 v34, v38, v34, vcc
	v_and_b32_e32 v34, 1, v34
	v_lshlrev_b32_e32 v3, 12, v77
	v_cmp_eq_u32_e64 s[24:25], 1, v34
	v_xor_b32_e32 v34, 0x3c00, v3
	v_cvt_f16_f32_e32 v116, v26
	v_cvt_f16_f32_e32 v63, v28
	v_cvt_pk_f16_f32 v49, v64, v65
	v_cvt_f16_f32_e32 v64, v29
	v_cvt_f16_f32_e32 v65, v14
	v_cvt_pk_f16_f32 v54, v58, v59
	v_cvt_f16_f32_e32 v55, v15
	v_cvt_f16_f32_e32 v58, v16
	v_cndmask_b32_e64 v34, v34, v3, s[12:13]
	v_xor_b32_e32 v3, 14, v61
	v_cndmask_b32_e64 v3, v3, v36, s[12:13]
	v_lshlrev_b32_e32 v36, 10, v3
	v_xor_b32_e32 v3, 13, v61
	v_cvt_pk_f16_f32 v67, v30, v31
	v_cvt_pk_f16_f32 v59, v24, v25
	v_cvt_pk_f16_f32 v69, v32, v33
	v_cndmask_b32_e64 v3, v3, v37, s[12:13]
	v_cvt_pk_f16_f32 v16, v93, v96
	v_cvt_pk_f16_f32 v15, v89, v91
	v_cvt_pk_f16_f32 v14, v85, v87
	v_cvt_pk_f16_f32 v25, v97, v101
	v_cvt_pk_f16_f32 v24, v92, v94
	v_cvt_pk_f16_f32 v23, v88, v90
	s_waitcnt vmcnt(2)
	v_cvt_pk_f16_f32 v29, v113, v115
	v_cvt_pk_f16_f32 v28, v109, v111
	v_cvt_pk_f16_f32 v26, v98, v102
	s_waitcnt vmcnt(0)
	v_cvt_pk_f16_f32 v33, v112, v114
	v_cvt_pk_f16_f32 v32, v108, v110
	v_cvt_pk_f16_f32 v31, v103, v106
	v_cvt_pk_f16_f32 v30, v95, v99
	v_add_u32_e32 v165, v82, v155
	v_cvt_f32_f16_e32 v82, v42
	v_cvt_f32_f16_sdwa v83, v42 dst_sel:DWORD dst_unused:UNUSED_PAD src0_sel:WORD_1
	v_cvt_f32_f16_e32 v84, v43
	v_cvt_f32_f16_sdwa v85, v43 dst_sel:DWORD dst_unused:UNUSED_PAD src0_sel:WORD_1
	v_cvt_f32_f16_e32 v86, v46
	v_cvt_f32_f16_sdwa v87, v46 dst_sel:DWORD dst_unused:UNUSED_PAD src0_sel:WORD_1
	v_cvt_f32_f16_e32 v88, v44
	v_cvt_f32_f16_sdwa v89, v44 dst_sel:DWORD dst_unused:UNUSED_PAD src0_sel:WORD_1
	v_cvt_f32_f16_e32 v90, v45
	v_cvt_f32_f16_sdwa v91, v45 dst_sel:DWORD dst_unused:UNUSED_PAD src0_sel:WORD_1
	v_cvt_f32_f16_e32 v92, v48
	v_cvt_f32_f16_sdwa v93, v48 dst_sel:DWORD dst_unused:UNUSED_PAD src0_sel:WORD_1
	v_cvt_f32_f16_e32 v94, v66
	v_cvt_f32_f16_sdwa v95, v66 dst_sel:DWORD dst_unused:UNUSED_PAD src0_sel:WORD_1
	v_cvt_f32_f16_e32 v96, v67
	v_cvt_f32_f16_sdwa v97, v67 dst_sel:DWORD dst_unused:UNUSED_PAD src0_sel:WORD_1
	v_cvt_f32_f16_e32 v98, v68
	v_cvt_f32_f16_sdwa v99, v68 dst_sel:DWORD dst_unused:UNUSED_PAD src0_sel:WORD_1
	v_cvt_f32_f16_e32 v100, v59
	v_cvt_f32_f16_sdwa v101, v59 dst_sel:DWORD dst_unused:UNUSED_PAD src0_sel:WORD_1
	v_cvt_f32_f16_e32 v102, v69
	v_cvt_f32_f16_sdwa v103, v69 dst_sel:DWORD dst_unused:UNUSED_PAD src0_sel:WORD_1
	v_cvt_f32_f16_e32 v174, v116
	v_cvt_f32_f16_e32 v175, v62
	v_cvt_f32_f16_e32 v176, v63
	v_cvt_f32_f16_e32 v177, v64
	v_cvt_f32_f16_e32 v178, v65
	v_cvt_f32_f16_e32 v179, v55
	v_cvt_f32_f16_e32 v180, v58
	v_cvt_f32_f16_e32 v181, v56
	v_cvt_f32_f16_e32 v106, v47
	v_cvt_f32_f16_sdwa v107, v47 dst_sel:DWORD dst_unused:UNUSED_PAD src0_sel:WORD_1
	v_cvt_f32_f16_e32 v108, v50
	v_cvt_f32_f16_sdwa v109, v50 dst_sel:DWORD dst_unused:UNUSED_PAD src0_sel:WORD_1
	v_cvt_f32_f16_e32 v110, v51
	v_cvt_f32_f16_sdwa v111, v51 dst_sel:DWORD dst_unused:UNUSED_PAD src0_sel:WORD_1
	v_cvt_f32_f16_e32 v112, v49
	v_cvt_f32_f16_sdwa v113, v49 dst_sel:DWORD dst_unused:UNUSED_PAD src0_sel:WORD_1
	v_cvt_f32_f16_e32 v114, v52
	v_cvt_f32_f16_sdwa v115, v52 dst_sel:DWORD dst_unused:UNUSED_PAD src0_sel:WORD_1
	v_cvt_f32_f16_e32 v116, v53
	v_cvt_f32_f16_sdwa v117, v53 dst_sel:DWORD dst_unused:UNUSED_PAD src0_sel:WORD_1
	v_cvt_f32_f16_e32 v122, v54
	v_cvt_f32_f16_sdwa v123, v54 dst_sel:DWORD dst_unused:UNUSED_PAD src0_sel:WORD_1
	v_cvt_f32_f16_e32 v126, v40
	v_cvt_f32_f16_sdwa v127, v40 dst_sel:DWORD dst_unused:UNUSED_PAD src0_sel:WORD_1
	v_cvt_f32_f16_e32 v128, v41
	v_cvt_f32_f16_sdwa v129, v41 dst_sel:DWORD dst_unused:UNUSED_PAD src0_sel:WORD_1
	v_lshlrev_b32_e32 v38, 10, v3
	v_xor_b32_e32 v3, 12, v61
	v_lshlrev_b32_e32 v173, 8, v57
	v_cndmask_b32_e64 v3, v3, v39, s[12:13]
	v_sub_u32_e32 v73, 0, v155
	v_mul_u32_u24_e32 v133, 0x280, v57
	v_or_b32_e32 v42, 0x800, v173
	v_lshlrev_b32_e32 v40, 10, v3
	v_mov_b32_e32 v46, 0
	s_mov_b32 s57, 0
	s_mov_b32 s62, 16
	v_mul_u32_u24_e32 v183, 0x90, v57
	v_cmp_eq_u32_e64 s[28:29], 1, v77
	v_cmp_eq_u32_e64 s[30:31], 2, v77
	v_cmp_eq_u32_e64 s[34:35], 3, v77
	v_add_u32_e32 v209, v166, v75
	v_add_u32_e32 v210, v161, v75
	s_movk_i32 s79, 0x8e0
	v_add_u32_e32 v211, v157, v42
	v_add_u32_e32 v212, v35, v5
	v_add_u32_e32 v213, v156, v60
	v_add_u32_e32 v214, v169, v76
	v_add_u32_e32 v215, v158, v73
	v_add_u32_e32 v216, v132, v160
	v_lshlrev_b32_e32 v130, 1, v34
	v_lshlrev_b32_e32 v132, 1, v36
	v_lshlrev_b32_e32 v134, 1, v38
	v_lshlrev_b32_e32 v136, 1, v40
	v_add_u32_e32 v217, v4, v133
	v_add_u32_e32 v218, 0x80, v131
	v_mov_b32_e32 v47, v46
	v_mov_b32_e32 v48, v46
	v_mov_b32_e32 v49, v46
	v_mov_b32_e32 v56, v46
	v_mov_b32_e32 v57, v46
	v_mov_b32_e32 v64, v46
	v_mov_b32_e32 v65, v46
	v_mov_b32_e32 v54, v46
	v_mov_b32_e32 v55, v46
	v_mov_b32_e32 v62, v46
	v_mov_b32_e32 v63, v46
	v_mov_b32_e32 v50, v46
	v_mov_b32_e32 v51, v46
	v_mov_b32_e32 v52, v46
	v_mov_b32_e32 v53, v46
	s_mov_b32 s78, 0xbfb8aa3b
	s_mov_b32 s66, 0xbf60028a
	v_mul_f32_e32 v194, s78, v1
	v_mul_f32_e32 v195, s78, v149
	v_and_b32_e32 v219, 15, v235
	v_lshrrev_b32_e32 v220, 4, v235
	v_sub_u32_e32 v221, 3, v220
	v_cndmask_b32_e64 v221, v221, v220, s[12:13]
	s_lshl_b32 s72, s45, 4
	v_add_u32_e32 v222, s72, v219
	v_lshlrev_b32_e32 v223, 2, v235
	v_sub_u32_e32 v223, v170, v223
	v_mul_u32_u24_e32 v189, 0x240, v221
	v_lshl_add_u32 v189, v222, 1, v189
	v_add_u32_e32 v189, v223, v189
	v_mul_u32_u24_e32 v190, 48, v222
	v_lshl_add_u32 v190, v221, 3, v190
	v_add_u32_e32 v190, v223, v190
	s_lshl_b32 s72, s45, 8
	v_lshl_add_u32 v191, v219, 4, s72
	v_add_u32_e32 v191, v223, v191
	v_lshl_add_u32 v192, v220, 2, v191
	v_lshl_add_u32 v193, v222, 2, v223
	v_and_b32_e32 v3, 1, v221
	v_cmp_ne_u32_e64 s[72:73], 0, v3
	v_and_b32_e32 v4, 2, v221
	v_cmp_ne_u32_e64 s[74:75], 0, v4
	s_waitcnt lgkmcnt(0)
	s_barrier
	s_branch .LBB0_181

.LBB0_217:
	s_nop 7
	s_waitcnt lgkmcnt(0)
	v_pk_fma_f32 v[42:43], v[66:67], s[78:79], v[194:195] op_sel_hi:[1,0,0]
	v_pk_fma_f32 v[44:45], v[68:69], s[78:79], v[194:195] op_sel_hi:[1,0,0]
	v_pk_fma_f32 v[38:39], v[70:71], s[78:79], v[194:195] op_sel:[0,0,1] op_sel_hi:[1,0,1]
	v_pk_fma_f32 v[40:41], v[72:73], s[78:79], v[194:195] op_sel:[0,0,1] op_sel_hi:[1,0,1]
	v_exp_f32_e32 v42, v42
	v_exp_f32_e32 v43, v43
	v_exp_f32_e32 v44, v44
	v_exp_f32_e32 v45, v45
	v_exp_f32_e32 v38, v38
	v_exp_f32_e32 v39, v39
	v_exp_f32_e32 v40, v40
	v_exp_f32_e32 v41, v41
	v_pk_add_f32 v[42:43], v[42:43], 1.0 op_sel_hi:[1,0]
	v_pk_add_f32 v[44:45], v[44:45], 1.0 op_sel_hi:[1,0]
	v_pk_add_f32 v[38:39], v[38:39], 1.0 op_sel_hi:[1,0]
	v_pk_add_f32 v[40:41], v[40:41], 1.0 op_sel_hi:[1,0]
	v_rcp_f32_e32 v42, v42
	v_rcp_f32_e32 v43, v43
	v_rcp_f32_e32 v44, v44
	v_rcp_f32_e32 v45, v45
	v_rcp_f32_e32 v38, v38
	v_rcp_f32_e32 v39, v39
	v_rcp_f32_e32 v40, v40
	v_rcp_f32_e32 v41, v41
	v_pk_mul_f32 v[246:247], v[74:75], v[152:153] op_sel_hi:[1,0]
	v_pk_mul_f32 v[248:249], v[76:77], v[152:153] op_sel_hi:[1,0]
	v_pk_mul_f32 v[42:43], v[42:43], s[66:67] op_sel_hi:[1,0]
	v_pk_mul_f32 v[44:45], v[44:45], s[66:67] op_sel_hi:[1,0]
	v_pk_mul_f32 v[246:247], v[246:247], v[58:59]
	v_pk_mul_f32 v[248:249], v[248:249], v[60:61]
	v_pk_add_f32 v[34:35], v[38:39], 1.0 op_sel_hi:[1,0] neg_lo:[0,1] neg_hi:[0,1]
	v_pk_add_f32 v[36:37], v[40:41], 1.0 op_sel_hi:[1,0] neg_lo:[0,1] neg_hi:[0,1]
	v_exp_f32_e32 v242, v42
	v_exp_f32_e32 v243, v43
	v_exp_f32_e32 v244, v44
	v_exp_f32_e32 v245, v45
	v_pk_fma_f32 v[34:35], v[152:153], v[34:35], 1.0 op_sel:[1,0,0] op_sel_hi:[1,1,0]
	v_pk_fma_f32 v[36:37], v[152:153], v[36:37], 1.0 op_sel:[1,0,0] op_sel_hi:[1,1,0]
	v_pk_mul_f32 v[250:251], v[246:247], v[38:39]
	v_pk_mul_f32 v[168:169], v[248:249], v[40:41]
	v_pk_mul_f32 v[34:35], v[74:75], v[34:35]
	v_pk_mul_f32 v[36:37], v[76:77], v[36:37]
	v_mul_f32_e32 v3, v242, v243
	v_mul_f32_e32 v4, v244, v245
	v_mul_f32_e32 v3, v3, v4
	ds_write_b32 v192, v3 offset:25216
	ds_read_b128 v[58:61], v191 offset:25216
	s_andn2_b64 vcc, exec, s[12:13]
	s_waitcnt lgkmcnt(0)
	s_cbranch_vccnz .Ls34_rev
	v_mul_f32_e32 v5, v58, v59
	s_nop 0
	v_rcp_f32_e32 v66, v5
	s_nop 0
	v_mul_f32_e32 v67, v66, v58
	v_mul_f32_e32 v68, v67, v59
	v_mul_f32_e32 v69, v68, v60
	v_mul_f32_e32 v70, v69, v61
	v_cndmask_b32_e64 v71, v66, v67, s[72:73]
	v_cndmask_b32_e64 v72, v68, v69, s[72:73]
	v_cndmask_b32_e64 v71, v71, v72, s[74:75]
	v_mul_f32_e32 v72, v71, v242
	v_mul_f32_e32 v73, v72, v243
	v_mul_f32_e32 v74, v73, v244
	v_mul_f32_e32 v75, v74, v245
	v_rcp_f32_e32 v38, v72
	v_rcp_f32_e32 v39, v73
	v_rcp_f32_e32 v40, v74
	v_rcp_f32_e32 v41, v75
	v_fma_mixlo_f16 v42, v71, v246, 0
	v_fma_mixhi_f16 v42, v72, v247, 0
	v_fma_mixlo_f16 v43, v73, v248, 0
	v_fma_mixhi_f16 v43, v74, v249, 0
	v_fma_mixlo_f16 v44, v250, v38, 0
	v_fma_mixhi_f16 v44, v251, v39, 0
	v_fma_mixlo_f16 v45, v168, v40, 0
	v_fma_mixhi_f16 v45, v169, v41, 0
	v_fma_mixlo_f16 v238, v34, v38, 0
	v_fma_mixhi_f16 v238, v35, v39, 0
	v_fma_mixlo_f16 v239, v36, v40, 0
	v_fma_mixhi_f16 v239, v37, v41, 0
	v_fma_mixlo_f16 v240, v72, v138, 0
	v_fma_mixhi_f16 v240, v73, v140, 0
	v_fma_mixlo_f16 v241, v74, v142, 0
	v_fma_mixhi_f16 v241, v75, v144, 0
	v_cvt_pk_f16_f32 v146, v139, v141
	v_cvt_pk_f16_f32 v147, v143, v145
	s_mov_b32 s76, 0x80008000
	v_xor_b32_e32 v76, s76, v44
	v_xor_b32_e32 v77, s76, v45
	ds_write_b16 v189, v42 offset:32640
	ds_write_b16_d16_hi v189, v42 offset:32784
	ds_write_b16 v189, v43 offset:32928
	ds_write_b16_d16_hi v189, v43 offset:33072
	ds_write_b16 v189, v44 offset:34944
	ds_write_b16_d16_hi v189, v44 offset:35088
	ds_write_b16 v189, v45 offset:35232
	ds_write_b16_d16_hi v189, v45 offset:35376
	ds_write_b16 v189, v238 offset:37248
	ds_write_b16_d16_hi v189, v238 offset:37392
	ds_write_b16 v189, v239 offset:37536
	ds_write_b16_d16_hi v189, v239 offset:37680
	ds_write_b16 v189, v240 offset:39552
	ds_write_b16_d16_hi v189, v240 offset:39696
	ds_write_b16 v189, v241 offset:39840
	ds_write_b16_d16_hi v189, v241 offset:39984
	ds_write_b64 v190, v[76:77] offset:41856
	ds_write_b64 v190, v[238:239] offset:44928
	ds_write_b64 v190, v[146:147] offset:48000
	s_mov_b64 s[76:77], exec
	s_mov_b64 exec, 0xffff
	ds_write_b32 v193, v5 offset:51072
	ds_write_b32 v193, v70 offset:51328
	s_mov_b64 exec, s[76:77]
	s_branch .LBB0_229
.Ls34_rev:
	v_mul_f32_e32 v5, v61, v60
	s_nop 0
	v_rcp_f32_e32 v66, v5
	s_nop 0
	v_mul_f32_e32 v67, v66, v61
	v_mul_f32_e32 v68, v67, v60
	v_mul_f32_e32 v69, v68, v59
	v_mul_f32_e32 v70, v69, v58
	v_cndmask_b32_e64 v71, v66, v67, s[72:73]
	v_cndmask_b32_e64 v72, v68, v69, s[72:73]
	v_cndmask_b32_e64 v71, v71, v72, s[74:75]
	v_mul_f32_e32 v72, v71, v245
	v_mul_f32_e32 v73, v72, v244
	v_mul_f32_e32 v74, v73, v243
	v_mul_f32_e32 v75, v74, v242
	v_rcp_f32_e32 v38, v72
	v_rcp_f32_e32 v39, v73
	v_rcp_f32_e32 v40, v74
	v_rcp_f32_e32 v41, v75
	v_fma_mixlo_f16 v42, v71, v249, 0
	v_fma_mixhi_f16 v42, v72, v248, 0
	v_fma_mixlo_f16 v43, v73, v247, 0
	v_fma_mixhi_f16 v43, v74, v246, 0
	v_fma_mixlo_f16 v44, v169, v38, 0
	v_fma_mixhi_f16 v44, v168, v39, 0
	v_fma_mixlo_f16 v45, v251, v40, 0
	v_fma_mixhi_f16 v45, v250, v41, 0
	v_fma_mixlo_f16 v238, v37, v38, 0
	v_fma_mixhi_f16 v238, v36, v39, 0
	v_fma_mixlo_f16 v239, v35, v40, 0
	v_fma_mixhi_f16 v239, v34, v41, 0
	v_fma_mixlo_f16 v240, v72, v144, 0
	v_fma_mixhi_f16 v240, v73, v142, 0
	v_fma_mixlo_f16 v241, v74, v140, 0
	v_fma_mixhi_f16 v241, v75, v138, 0
	v_cvt_pk_f16_f32 v146, v145, v143
	v_cvt_pk_f16_f32 v147, v141, v139
	s_mov_b32 s76, 0x80008000
	v_xor_b32_e32 v76, s76, v44
	v_xor_b32_e32 v77, s76, v45
	ds_write_b16 v189, v42 offset:32640
	ds_write_b16_d16_hi v189, v42 offset:32784
	ds_write_b16 v189, v43 offset:32928
	ds_write_b16_d16_hi v189, v43 offset:33072
	ds_write_b16 v189, v44 offset:34944
	ds_write_b16_d16_hi v189, v44 offset:35088
	ds_write_b16 v189, v45 offset:35232
	ds_write_b16_d16_hi v189, v45 offset:35376
	ds_write_b16 v189, v238 offset:37248
	ds_write_b16_d16_hi v189, v238 offset:37392
	ds_write_b16 v189, v239 offset:37536
	ds_write_b16_d16_hi v189, v239 offset:37680
	ds_write_b16 v189, v240 offset:39552
	ds_write_b16_d16_hi v189, v240 offset:39696
	ds_write_b16 v189, v241 offset:39840
	ds_write_b16_d16_hi v189, v241 offset:39984
	ds_write_b64 v190, v[76:77] offset:41856
	ds_write_b64 v190, v[238:239] offset:44928
	ds_write_b64 v190, v[146:147] offset:48000
	s_mov_b64 s[76:77], exec
	s_mov_b64 exec, 0xffff
	ds_write_b32 v193, v5 offset:51072
	ds_write_b32 v193, v70 offset:51328
	s_mov_b64 exec, s[76:77]
